# GEMM prologue de-serialised: K-tile 1 DMA loads issued before waiting on K-tile 0 (both GEMM instantiations), on top of v11
# speedup vs baseline: 1.0034x; 1.0034x over previous
.LBB0_358:
	v_lshlrev_b32_e32 v13, 2, v189
	v_lshl_or_b32 v194, s3, 6, v189
	v_lshl_or_b32 v12, v189, 6, v191
	s_lshl_b32 s3, s3, 13
	v_and_b32_e32 v13, 32, v13
	s_add_i32 m0, s45, 0x18000
	v_lshl_add_u64 v[0:1], v[0:1], 0, s[36:37]
	v_bitop3_b32 v12, v12, s3, v13 bitop3:0xde
	s_lshl_b32 s3, s10, 5
	global_load_lds_dwordx4 v[0:1], off
	v_lshl_add_u64 v[0:1], v[2:3], 0, s[36:37]
	s_add_i32 m0, s45, 0x1a000
	s_add_i32 s10, s45, 0x8000
	global_load_lds_dwordx4 v[0:1], off
	v_lshl_add_u64 v[0:1], v[8:9], 0, s[36:37]
	s_mov_b32 m0, s10
	s_add_i32 s11, s45, 0xa000
	global_load_lds_dwordx4 v[0:1], off
	v_lshl_add_u64 v[0:1], v[10:11], 0, s[36:37]
	s_mov_b32 m0, s11
	s_and_b32 s3, s3, 0x60
	global_load_lds_dwordx4 v[0:1], off
	s_add_i32 m0, s45, 0x1c000
	v_lshl_add_u64 v[0:1], v[4:5], 0, s[36:37]
	global_load_lds_dwordx4 v[0:1], off
	v_lshl_add_u64 v[0:1], v[6:7], 0, s[36:37]
	s_add_i32 m0, s45, 0x1e000
	s_add_i32 s13, s31, -2
	global_load_lds_dwordx4 v[0:1], off
	s_cmpk_lt_u32 s2, 0x100
	v_lshl_or_b32 v195, s3, 7, v192
	s_cselect_b64 s[74:75], -1, 0
	v_or_b32_e32 v196, s3, v190
	s_lshl_b32 s3, s82, 3
	v_cvt_f32_u32_e32 v0, s3
	s_lshr_b32 s2, s73, 3
	s_and_b32 s85, s73, 6
	s_add_i32 s58, s2, 1
	v_rcp_iflag_f32_e32 v0, v0
	s_cmp_lg_u64 s[42:43], 0
	s_cselect_b64 s[90:91], -1, 0
	s_cselect_b32 s100, s42, s88
	s_cselect_b32 s101, s43, s89
	s_sub_i32 s14, 0, s3
	v_mul_f32_e32 v0, 0x4f7ffffe, v0
	v_cvt_u32_f32_e32 v0, v0
	s_waitcnt vmcnt(8)
	s_barrier
	s_waitcnt vmcnt(6)
	v_mov_b32_e32 v157, v155
	s_mov_b32 s84, s2
	v_readfirstlane_b32 s15, v0
	s_mul_i32 s14, s14, s15
	s_mul_hi_u32 s14, s15, s14
	v_lshl_add_u64 v[164:165], s[42:43], 0, v[156:157]
	s_mov_b32 s18, 0
	s_add_i32 s33, s15, s14
	v_lshl_add_u64 v[166:167], s[8:9], 0, v[158:159]
	v_lshl_add_u64 v[168:169], s[8:9], 0, v[160:161]
	v_add_u32_e32 v157, 0, v12
	s_movk_i32 s69, 0x2000
	s_barrier
	v_lshlrev_b32_e32 v248, 4, v199
	s_branch .LBB0_361

.LBB0_465:
	s_add_i32 m0, s3, 0x18000
	v_lshl_add_u64 v[0:1], v[0:1], 0, s[36:37]
	v_lshl_or_b32 v164, s18, 6, v189
	s_lshl_b32 s14, s18, 13
	global_load_lds_dwordx4 v[0:1], off
	v_lshl_add_u64 v[0:1], v[2:3], 0, s[36:37]
	s_add_i32 m0, s3, 0x1a000
	s_add_i32 s18, s3, 0x8000
	global_load_lds_dwordx4 v[0:1], off
	v_lshl_add_u64 v[0:1], v[8:9], 0, s[36:37]
	s_mov_b32 m0, s18
	s_add_i32 s28, s3, 0xa000
	global_load_lds_dwordx4 v[0:1], off
	v_lshl_add_u64 v[0:1], v[10:11], 0, s[36:37]
	s_mov_b32 m0, s28
	s_and_b32 s17, s17, 3
	global_load_lds_dwordx4 v[0:1], off
	s_add_i32 m0, s3, 0x1c000
	v_lshl_add_u64 v[0:1], v[4:5], 0, s[36:37]
	global_load_lds_dwordx4 v[0:1], off
	v_lshl_add_u64 v[0:1], v[6:7], 0, s[36:37]
	s_add_i32 m0, s3, 0x1e000
	s_add_i32 s29, s31, -2
	global_load_lds_dwordx4 v[0:1], off
	s_cmpk_lt_u32 s23, 0x100
	s_cselect_b64 s[66:67], -1, 0
	s_lshl_b32 s16, s82, 3
	v_cvt_f32_u32_e32 v0, s16
	s_lshr_b32 s33, s73, 3
	s_and_b32 s58, s73, 6
	s_add_i32 s85, s33, 1
	v_rcp_iflag_f32_e32 v0, v0
	v_lshlrev_b32_e32 v13, 2, v189
	s_cmp_lg_u64 s[86:87], 0
	v_lshl_or_b32 v12, v189, 6, v191
	v_mul_f32_e32 v0, 0x4f7ffffe, v0
	v_cvt_u32_f32_e32 v0, v0
	v_and_b32_e32 v13, 32, v13
	s_cselect_b64 s[68:69], -1, 0
	s_cmp_lg_u64 s[50:51], 0
	v_bitop3_b32 v12, v12, s14, v13 bitop3:0xde
	s_cselect_b64 s[70:71], -1, 0
	s_sub_i32 s14, 0, s16
	v_readfirstlane_b32 s15, v0
	s_waitcnt vmcnt(8)
	s_barrier
	s_waitcnt vmcnt(6)
	s_mul_i32 s14, s14, s15
	s_mul_hi_u32 s14, s15, s14
	v_lshl_or_b32 v165, s17, 12, v192
	v_lshl_or_b32 v166, s17, 5, v190
	s_mov_b32 s92, 0
	s_add_i32 s93, s15, s14
	v_lshl_add_u64 v[142:143], s[8:9], 0, v[136:137]
	v_lshl_add_u64 v[144:145], s[8:9], 0, v[138:139]
	v_add_u32_e32 v167, 0, v12
	s_barrier
	s_branch .LBB0_468
